# combination: sign-tagged row-stat exchange + in-flight A-panel gate reads + static first mixer ticket, on top of the barrier/census/silu-table changes
# speedup vs baseline: 1.0062x; 1.0035x over previous
.Lrsx_init_done:
	v_cmp_gt_i32_e32 vcc, s12, v2
	s_and_saveexec_b64 s[12:13], vcc
	s_cbranch_execz .LBB0_11
	s_load_dwordx2 s[18:19], s[16:17], 0x8
	v_lshlrev_b32_e32 v3, 2, v2
	v_lshl_add_u32 v1, v2, 2, 0
	v_add_u32_e32 v6, 0x1000, v3
	v_add_u32_e32 v7, 0x2000, v3
	v_add_u32_e32 v8, 0x3000, v3
	s_waitcnt lgkmcnt(0)
	global_load_dword v16, v3, s[18:19]
	global_load_dword v17, v3, s[18:19] offset:2048
	global_load_dword v18, v6, s[18:19]
	global_load_dword v19, v6, s[18:19] offset:2048
	global_load_dword v20, v7, s[18:19]
	global_load_dword v21, v7, s[18:19] offset:2048
	global_load_dword v22, v8, s[18:19]
	global_load_dword v23, v8, s[18:19] offset:2048
	global_load_dword v24, v3, s[4:5]
	global_load_dword v25, v3, s[4:5] offset:2048
	s_waitcnt vmcnt(9)
	v_mul_f32_e32 v9, 0xbfb8aa3b, v16
	v_exp_f32_e32 v9, v9
	s_nop 0
	v_add_f32_e32 v9, 1.0, v9
	v_rcp_f32_e32 v9, v9
	s_nop 0
	v_mul_f32_e32 v16, v16, v9
	ds_write_b32 v1, v16
	s_waitcnt vmcnt(8)
	v_mul_f32_e32 v9, 0xbfb8aa3b, v17
	v_exp_f32_e32 v9, v9
	s_nop 0
	v_add_f32_e32 v9, 1.0, v9
	v_rcp_f32_e32 v9, v9
	s_nop 0
	v_mul_f32_e32 v17, v17, v9
	ds_write_b32 v1, v17 offset:2048
	s_waitcnt vmcnt(7)
	v_mul_f32_e32 v9, 0xbfb8aa3b, v18
	v_exp_f32_e32 v9, v9
	s_nop 0
	v_add_f32_e32 v9, 1.0, v9
	v_rcp_f32_e32 v9, v9
	s_nop 0
	v_mul_f32_e32 v18, v18, v9
	ds_write_b32 v1, v18 offset:4096
	s_waitcnt vmcnt(6)
	v_mul_f32_e32 v9, 0xbfb8aa3b, v19
	v_exp_f32_e32 v9, v9
	s_nop 0
	v_add_f32_e32 v9, 1.0, v9
	v_rcp_f32_e32 v9, v9
	s_nop 0
	v_mul_f32_e32 v19, v19, v9
	ds_write_b32 v1, v19 offset:6144
	s_waitcnt vmcnt(5)
	v_mul_f32_e32 v9, 0xbfb8aa3b, v20
	v_exp_f32_e32 v9, v9
	s_nop 0
	v_add_f32_e32 v9, 1.0, v9
	v_rcp_f32_e32 v9, v9
	s_nop 0
	v_mul_f32_e32 v20, v20, v9
	ds_write_b32 v1, v20 offset:8192
	s_waitcnt vmcnt(4)
	v_mul_f32_e32 v9, 0xbfb8aa3b, v21
	v_exp_f32_e32 v9, v9
	s_nop 0
	v_add_f32_e32 v9, 1.0, v9
	v_rcp_f32_e32 v9, v9
	s_nop 0
	v_mul_f32_e32 v21, v21, v9
	ds_write_b32 v1, v21 offset:10240
	s_waitcnt vmcnt(3)
	v_mul_f32_e32 v9, 0xbfb8aa3b, v22
	v_exp_f32_e32 v9, v9
	s_nop 0
	v_add_f32_e32 v9, 1.0, v9
	v_rcp_f32_e32 v9, v9
	s_nop 0
	v_mul_f32_e32 v22, v22, v9
	ds_write_b32 v1, v22 offset:12288
	s_waitcnt vmcnt(2)
	v_mul_f32_e32 v9, 0xbfb8aa3b, v23
	v_exp_f32_e32 v9, v9
	s_nop 0
	v_add_f32_e32 v9, 1.0, v9
	v_rcp_f32_e32 v9, v9
	s_nop 0
	v_mul_f32_e32 v23, v23, v9
	ds_write_b32 v1, v23 offset:14336
	s_waitcnt vmcnt(1)
	v_mul_f32_e32 v9, 0xbfb8aa3b, v24
	v_exp_f32_e32 v9, v9
	s_nop 0
	v_add_f32_e32 v9, 1.0, v9
	v_rcp_f32_e32 v9, v9
	s_nop 0
	v_mul_f32_e32 v24, v24, v9
	ds_write_b32 v1, v24 offset:16384
	s_waitcnt vmcnt(0)
	v_mul_f32_e32 v9, 0xbfb8aa3b, v25
	v_exp_f32_e32 v9, v9
	s_nop 0
	v_add_f32_e32 v9, 1.0, v9
	v_rcp_f32_e32 v9, v9
	s_nop 0
	v_mul_f32_e32 v25, v25, v9
	ds_write_b32 v1, v25 offset:18432
